# odd XCD pairs run their attention q-blocks in the opposite order (long units first) on top of pair barrier + P1 rotation
# speedup vs baseline: 1.0034x; 1.0034x over previous
; template<int THRL> __device__ __forceinline__ void attn_unit(int b,int hq,int vcol,int qb,const bf16*Q,const bf16*__restrict__ K,const bf16*__restrict__ V,bf16*O,char*shm){
;     ...
;   const long rowbase=(long)b*SEQ; const int q0=qb*QB;
;   const bf16*Qw=Q+(rowbase+q0+wid*QBLK)*DM+hq*D;
;   const bf16*Kh=K+rowbase*DM+hq*D,*Vh=V+rowbase*DM+vcol;
;   const unsigned lds0=(unsigned)(uintptr_t)shm;
;   float*wsf=(float*)(shm+LDS_WS)+wid*64;
;   const bf16*ksrc=Kh+(long)lane*DM+wid*8;
;   const bf16*vsrc=Vh+(long)(16*(wid&3)+(lane>>2))*DM+(wid>>2)*32+(lane&3)*8;
;   const unsigned kdst=lds0+LDS_K+wid*1024, vdst=lds0+LDS_V+wid*1024;
;     ...
;   const int vb0=(int)(lds0+LDS_V)+((lane>>4)&1)*32+(lane&3)*8+(4*hi+((lane&15)>>2))*64;
;   const char*Kbase=shm+LDS_K; bf16x8 kf[8];
;   const lds_cptr shm3=(lds_cptr)shm; const lds_cptr kp0=shm3+LDS_K+hi*1024+r32*16; const lds_cptr vp0=shm3+LDS_V+((lane>>4)&1)*32+(lane&3)*8+(4*hi+((lane&15)>>2))*64;
;   const int NT=(q0+QB)/KVBLK;
; __global__ void __launch_bounds__(NWAVES * 64, 2) mk_fwd(Args a) {
;     ...
;             for (int gidx = vcup; gidx < 512; gidx += G) {
;                 const int gi = gidx >> 8, v = gidx & 255, bh = v >> 3, s = v & 7, qb = gi ? 15 - s : s, b = bh >> 3, h = bh & 7;
; #pragma unroll 1
;                 for (int m = 0; m < 2; ++m) {
;                     if (ucount == convslot) { conv_items(BGb, CGb, conv_w + (size_t)l * 3 * DMOD, vcup, G); conv_done = true; }
;                     ++ucount;
;                     attn_body::attn_unit<8>(b, 2 * h + m, 128 * h, qb, (const attn_body::bf16*)Qb, (const attn_body::bf16*)Kb, (const attn_body::bf16*)Vb, (attn_body::bf16*)(m ? O2 : O1), (char*)lds);
.LBB0_249:
	s_lshl_b32 s1, s77, 1
	s_bfe_u32 s2, s78, 0x20006
	s_and_b32 s1, s1, 0x700
	s_lshl_b32 s3, s2, 23
	s_or_b32 s4, s3, s1
	s_and_b32 s1, s78, 7
	s_xor_b32 s12, s1, 15
	s_cmpk_lt_u32 s78, 0x100
	s_cselect_b32 s12, s1, s12
	v_readlane_b32 s1, v253, 1
	s_nop 3
	s_bfe_u32 s1, s1, 0x10001
	s_mul_i32 s1, s1, 15
	s_xor_b32 s12, s12, s1
	s_lshl_b32 s1, s78, 4
	s_lshl_b32 s80, s2, 12
	s_lshl_b32 s81, s12, 8
	s_and_b32 s79, s1, 0x380
	s_or_b32 s82, s81, s80
	v_readlane_b32 s1, v255, 8
	s_add_u32 s83, s1, s3
	v_readlane_b32 s1, v255, 9
	s_addc_u32 s1, s1, 0
	v_readlane_b32 s2, v255, 10
	s_add_u32 s2, s2, s3
	v_readlane_b32 s3, v255, 11
	s_addc_u32 s3, s3, 0
	s_lshl_b32 s13, s79, 1
	s_add_u32 s34, s2, s13
	s_addc_u32 s35, s3, 0
	s_add_i32 s2, s81, 0x100
	s_lshr_b32 s68, s2, 6
	v_readlane_b32 s2, v253, 18
	v_readlane_b32 s3, v253, 19
	s_load_dwordx8 s[20:27], s[2:3], 0x80
	s_cmp_eq_u32 s12, 0
	s_cselect_b64 s[42:43], -1, 0
	s_cmp_lg_u32 s12, 0
	s_cselect_b64 s[52:53], -1, 0
	s_waitcnt lgkmcnt(0)
	s_add_u32 s20, s26, s4
	s_addc_u32 s21, s27, 0
	s_lshl_b32 s2, s12, 2
	s_sub_i32 s69, 0, s2
	s_mov_b64 s[36:37], -1
	s_mov_b32 s13, s64
	s_mov_b32 s4, 0
	s_movk_i32 s26, 0x400
	s_branch .LBB0_251
